# m13 + per-XCC start stagger (bx%8 x s_sleep 28) at the FFN-up phase entry, to spread the epilogue store bursts of the eight XCCs over time
# baseline (speedup 1.0000x reference)
.LBB0_409:
	s_and_b64 s[0:1], s[46:47], exec
	s_cselect_b32 s54, 2, 10
	v_readlane_b32 s6, v253, 8
	v_readlane_b32 s7, v253, 9
	s_cmp_le_i32 s6, s54
	s_cselect_b64 s[0:1], -1, 0
	s_cmp_lt_i32 s54, s7
	s_cselect_b64 s[6:7], -1, 0
	s_and_b64 s[0:1], s[0:1], s[6:7]
	s_andn2_b64 vcc, exec, s[0:1]
	s_cbranch_vccnz .LBB0_508
	s_and_b32 s0, s2, 7
	s_cmp_eq_u32 s0, 0
	s_cbranch_scc1 .Lstag_done
.Lstag_loop:
	s_sleep 28
	s_add_i32 s0, s0, -1
	s_cmp_lg_u32 s0, 0
	s_cbranch_scc1 .Lstag_loop
.Lstag_done:
	v_readlane_b32 s0, v253, 0
	s_mov_b64 s[6:7], s[72:73]
	v_readlane_b32 s1, v253, 1
	v_mov_b32_e32 v2, v0
	v_readlane_b32 s0, v253, 14
	v_mov_b32_e32 v10, v0
	v_readlane_b32 s1, v253, 15
	s_andn2_b64 vcc, exec, s[0:1]
	v_readfirstlane_b32 s10, v10
	s_cbranch_vccnz .LBB0_426
	v_lshlrev_b32_e32 v2, 4, v10
	v_add_u32_e32 v3, 0x2000, v2
	v_ashrrev_i32_e32 v4, 31, v3
	v_lshrrev_b32_e32 v4, 22, v4
	v_add_u32_e32 v4, v3, v4
	v_ashrrev_i32_e32 v11, 10, v4
	v_mul_i32_i24_e32 v4, 0x400, v11
	s_and_b64 s[0:1], s[46:47], exec
	v_sub_u32_e32 v3, v3, v4
	s_mov_b32 s0, 0xac00000
	v_lshrrev_b32_e32 v4, 4, v3
	s_cselect_b32 s0, s0, 0x3400000
	v_bitop3_b32 v3, v4, v3, 32 bitop3:0x6c
	s_add_u32 s12, s6, s0
	v_ashrrev_i32_e32 v4, 31, v3
	s_addc_u32 s13, s7, 0
	v_lshrrev_b32_e32 v4, 26, v4
	s_and_b64 s[0:1], s[46:47], exec
	v_add_u32_e32 v4, v3, v4
	v_lshlrev_b32_e32 v5, 3, v11
	s_mov_b32 s0, 0x200000
	v_ashrrev_i32_e32 v12, 6, v4
	v_and_b32_e32 v5, -16, v5
	s_cselect_b32 s0, s0, 0x2100000
	v_add_u32_e32 v5, v12, v5
	s_add_u32 s14, s6, s0
	v_and_b32_e32 v6, 3, v12
	s_mov_b32 s0, 0x1fffe0
	v_lshrrev_b32_e32 v7, 2, v5
	v_lshlrev_b32_e32 v8, 1, v5
	v_and_b32_e32 v4, 0xc0, v4
	v_and_or_b32 v6, v5, s0, v6
	v_and_b32_e32 v7, 4, v7
	v_and_b32_e32 v8, 24, v8
	v_sub_u32_e32 v3, v3, v4
	v_or3_b32 v6, v6, v7, v8
	v_lshlrev_b32_e32 v7, 5, v11
	v_ashrrev_i16_sdwa v3, v186, sext(v3) dst_sel:DWORD dst_unused:UNUSED_PAD src0_sel:DWORD src1_sel:BYTE_0
	v_and_b32_e32 v7, 32, v7
	v_bfe_i32 v13, v3, 0, 16
	v_add_lshl_u32 v3, v7, v13, 1
	v_lshl_add_u32 v130, v6, 11, v3
	v_lshl_add_u32 v132, v5, 11, v3
	v_bfe_i32 v3, v10, 27, 1
	v_lshrrev_b32_e32 v3, 22, v3
	v_add_u32_e32 v3, v2, v3
	v_and_b32_e32 v3, 0xfffffc00, v3
	v_sub_u32_e32 v2, v2, v3
	v_lshrrev_b32_e32 v3, 4, v2
	v_ashrrev_i32_e32 v4, 31, v10
	v_bitop3_b32 v2, v3, v2, 32 bitop3:0x6c
	v_lshrrev_b32_e32 v4, 26, v4
	v_ashrrev_i32_e32 v3, 31, v2
	v_add_u32_e32 v4, v10, v4
	v_lshrrev_b32_e32 v3, 26, v3
	v_ashrrev_i32_e32 v15, 6, v4
	v_add_u32_e32 v3, v2, v3
	v_lshlrev_b32_e32 v4, 3, v15
	v_ashrrev_i32_e32 v14, 6, v3
	v_and_b32_e32 v4, -16, v4
	v_add_u32_e32 v4, v14, v4
	v_and_b32_e32 v5, 3, v14
	v_lshrrev_b32_e32 v6, 2, v4
	v_lshlrev_b32_e32 v7, 1, v4
	v_and_b32_e32 v3, 0xc0, v3
	s_addc_u32 s15, s7, 0
	s_ashr_i32 s21, s10, 6
	v_and_or_b32 v5, v4, s0, v5
	v_and_b32_e32 v6, 4, v6
	v_and_b32_e32 v7, 24, v7
	v_sub_u32_e32 v2, v2, v3
	s_ashr_i32 s11, s10, 8
	s_lshl_b32 s16, s21, 10
	v_or3_b32 v5, v5, v6, v7
	v_lshlrev_b32_e32 v6, 5, v15
	v_ashrrev_i16_sdwa v2, v186, sext(v2) dst_sel:DWORD dst_unused:UNUSED_PAD src0_sel:DWORD src1_sel:BYTE_0
	v_readlane_b32 s0, v252, 48
	v_and_b32_e32 v6, 32, v6
	v_bfe_i32 v16, v2, 0, 16
	v_readlane_b32 s1, v252, 49
	s_add_u32 s0, s14, s0
	v_add_lshl_u32 v2, v6, v16, 1
	s_addc_u32 s1, s15, s1
	s_add_i32 s17, s16, 0
	v_lshl_add_u32 v188, v5, 11, v2
	s_add_i32 m0, s17, 0x10000
	v_lshl_add_u32 v134, v4, 11, v2
	global_load_lds_dwordx4 v188, s[0:1]
	s_add_i32 m0, s17, 0x12000
	s_add_u32 s8, s0, 0x40000
	global_load_lds_dwordx4 v130, s[0:1]
	s_addc_u32 s9, s1, 0
	s_add_i32 m0, s17, 0x14000
	v_mov_b32_e32 v131, v189
	global_load_lds_dwordx4 v188, s[8:9]
	s_add_i32 m0, s17, 0x16000
	v_mov_b32_e32 v135, v189
	global_load_lds_dwordx4 v130, s[8:9]
	v_readlane_b32 s8, v252, 53
	v_readlane_b32 s9, v252, 54
	s_add_u32 s8, s12, s8
	s_addc_u32 s9, s13, s9
	s_add_i32 s18, s17, 0x2000
	s_mov_b32 m0, s17
	s_add_u32 s24, s8, 0x40000
	global_load_lds_dwordx4 v134, s[8:9]
	s_mov_b32 m0, s18
	s_addc_u32 s25, s9, 0
	s_add_i32 s19, s17, 0x4000
	global_load_lds_dwordx4 v132, s[8:9]
	s_mov_b32 m0, s19
	s_add_i32 s20, s17, 0x6000
	global_load_lds_dwordx4 v134, s[24:25]
	s_mov_b32 m0, s20
	v_mov_b32_e32 v133, v189
	global_load_lds_dwordx4 v132, s[24:25]
	s_cmp_eq_u32 s11, 1
	v_lshl_add_u64 v[8:9], s[0:1], 0, v[188:189]
	v_lshl_add_u64 v[6:7], s[0:1], 0, v[130:131]
	v_lshl_add_u64 v[2:3], s[8:9], 0, v[134:135]
	s_cselect_b64 s[40:41], -1, 0
	s_cmp_lg_u32 s11, 1
	v_lshl_add_u64 v[4:5], s[8:9], 0, v[132:133]
	s_cbranch_scc1 .LBB0_413
	s_barrier
